# snake (Gray-code) MFMA issue order inside each 8-MFMA group of the FFN up K-loops: one operand changes per MFMA
# baseline (speedup 1.0000x reference)
; #define PG8_STAGE(bufoff, gbase, voff) do { _Pragma("unroll") for (int _i = 0; _i < 2; ++_i) \
;         asm volatile("s_mov_b32 m0, %0\n\ts_nop 0\n\tglobal_load_lds_dwordx4 %1, %2" :: "s"(ldsb + (unsigned)(bufoff) + ldsw + (unsigned)(_i * 8192)), "v"((voff)[_i]), "s"((const char*)(gbase)) : "memory", "m0"); } while (0)
; #define PG8_LDA(dst, b, h) do { _Pragma("unroll") for (int m = 0; m < 4; ++m) _Pragma("unroll") for (int k = 0; k < 2; ++k) dst[m][k] = *(const LAS bf16x8*)(lds + PG8_SA(b, h) + aoff + m * 2048 + k * 1024); } while (0)
; #define PG8_LDB(dst, b, h) do { _Pragma("unroll") for (int n = 0; n < 2; ++n) _Pragma("unroll") for (int k = 0; k < 2; ++k) dst[n][k] = *(const LAS bf16x8*)(lds + PG8_SB(b, h) + boff + n * 2048 + k * 1024); } while (0)
; #define PG8_MMA(ai, bj, At, Bt) do { __builtin_amdgcn_s_setprio(1); _Pragma("unroll") for (int m = 0; m < 4; ++m) _Pragma("unroll") for (int n = 0; n < 2; ++n) _Pragma("unroll") for (int k = 0; k < 2; ++k) \
;         acc[ai][bj][m][n] = __builtin_amdgcn_mfma_f32_16x16x32_bf16(Bt[n][k], At[m][k], acc[ai][bj][m][n], 0, 0, 0); __builtin_amdgcn_s_setprio(0); } while (0)
; #define PG8_WAIT_V(n) asm volatile("s_waitcnt vmcnt(" #n ")" ::: "memory")
; template <class Epi, class Sched>
; __device__ __forceinline__ void gemm_phase(LAS unsigned char* lds, const Gemm g, const Sched& S, const Epi& E) {
;     ...
;             PG8_LDB(B0, 0, 0); PG8_LDB(B1, 0, 1); PG8_SCHED; PG8_LDA(At, 0, 0); PG8_STAGE(PG8_SA(1, 1), a1 + hstepA, voffA);
;             PG8_WAIT_V(8); PG8_WAIT_L(0); PG8_BAR; PG8_MMA(0, 0, At, B0); PG8_MMA(0, 1, At, B1); PG8_BAR; PG8_SCHED;
;             PG8_LDA(At, 0, 1); PG8_STAGE(PG8_SB(0, 0), b2, voffB); PG8_STAGE(PG8_SB(0, 1), b2 + hstepB, voffB); PG8_STAGE(PG8_SA(0, 0), a2, voffA);
;             PG8_WAIT_V(8); PG8_WAIT_L(0); PG8_BAR; PG8_MMA(1, 0, At, B0); PG8_MMA(1, 1, At, B1); PG8_BAR; PG8_SCHED;
;             PG8_LDB(B0, 1, 0); PG8_LDB(B1, 1, 1); PG8_SCHED; PG8_LDA(At, 1, 0); PG8_STAGE(PG8_SA(0, 1), a2 + hstepA, voffA);
;             PG8_WAIT_V(8); PG8_WAIT_L(0); PG8_BAR; PG8_MMA(0, 0, At, B0); PG8_MMA(0, 1, At, B1); PG8_BAR; PG8_SCHED;
;             PG8_LDA(At, 1, 1); PG8_STAGE(PG8_SB(1, 0), b3, voffB); PG8_STAGE(PG8_SB(1, 1), b3 + hstepB, voffB); PG8_STAGE(PG8_SA(1, 0), a3, voffA);
;             PG8_WAIT_V(8); PG8_WAIT_L(0); PG8_BAR; PG8_MMA(1, 0, At, B0); PG8_MMA(1, 1, At, B1); PG8_BAR; PG8_SCHED;
.LBB0_168:
	ds_read_b128 v[144:147], v138
	ds_read_b128 v[148:151], v138 offset:1024
	ds_read_b128 v[152:155], v138 offset:2048
	ds_read_b128 v[156:159], v138 offset:3072
	ds_read_b128 v[160:163], v139
	ds_read_b128 v[164:167], v139 offset:1024
	ds_read_b128 v[168:171], v139 offset:2048
	ds_read_b128 v[172:175], v139 offset:3072
	s_cmp_eq_u32 s42, 28
	s_cselect_b32 s54, s15, s38
	s_cselect_b32 s55, s11, s39
	s_cselect_b32 s52, s74, s40
	s_cselect_b32 s53, s13, s41
	s_add_u32 s44, s54, 0x80
	s_addc_u32 s45, s55, 0
	ds_read_b128 v[176:179], v140
	ds_read_b128 v[184:187], v140 offset:1024
	ds_read_b128 v[188:191], v140 offset:2048
	ds_read_b128 v[192:195], v140 offset:3072
	ds_read_b128 v[196:199], v140 offset:4096
	ds_read_b128 v[200:203], v140 offset:5120
	ds_read_b128 v[204:207], v140 offset:6144
	ds_read_b128 v[212:215], v140 offset:7168
	s_add_u32 s46, s38, 0xffffff80
	s_addc_u32 s47, s39, -1
	s_mov_b32 m0, s66
	s_nop 0
	global_load_lds_dwordx4 v132, s[46:47]
	s_mov_b32 m0, s67
	s_nop 0
	global_load_lds_dwordx4 v134, s[46:47]
	s_add_u32 s46, s38, 0x7ff80
	s_addc_u32 s47, s39, 0
	s_mov_b32 m0, s70
	s_nop 0
	global_load_lds_dwordx4 v132, s[46:47]
	s_nop 0
	s_mov_b32 m0, s71
	s_nop 0
	global_load_lds_dwordx4 v134, s[46:47]
	s_waitcnt vmcnt(8)
	s_waitcnt lgkmcnt(0)
	s_barrier
	s_setprio 1
	s_waitcnt lgkmcnt(7)
	v_mfma_f32_16x16x32_bf16 v[122:125], v[144:147], v[176:179], v[122:125]
	v_mfma_f32_16x16x32_bf16 v[114:117], v[152:155], v[176:179], v[114:117]
	s_waitcnt lgkmcnt(5)
	v_mfma_f32_16x16x32_bf16 v[106:109], v[152:155], v[188:191], v[106:109]
	v_mfma_f32_16x16x32_bf16 v[110:113], v[144:147], v[188:191], v[110:113]
	s_waitcnt lgkmcnt(3)
	v_mfma_f32_16x16x32_bf16 v[78:81], v[144:147], v[196:199], v[78:81]
	v_mfma_f32_16x16x32_bf16 v[66:69], v[152:155], v[196:199], v[66:69]
	s_waitcnt lgkmcnt(1)
	v_mfma_f32_16x16x32_bf16 v[26:29], v[152:155], v[204:207], v[26:29]
	v_mfma_f32_16x16x32_bf16 v[38:41], v[144:147], v[204:207], v[38:41]
	v_mfma_f32_16x16x32_bf16 v[122:125], v[148:151], v[184:187], v[122:125]
	v_mfma_f32_16x16x32_bf16 v[114:117], v[156:159], v[184:187], v[114:117]
	v_mfma_f32_16x16x32_bf16 v[106:109], v[156:159], v[192:195], v[106:109]
	v_mfma_f32_16x16x32_bf16 v[110:113], v[148:151], v[192:195], v[110:113]
	v_mfma_f32_16x16x32_bf16 v[78:81], v[148:151], v[200:203], v[78:81]
	v_mfma_f32_16x16x32_bf16 v[66:69], v[156:159], v[200:203], v[66:69]
	s_waitcnt lgkmcnt(0)
	v_mfma_f32_16x16x32_bf16 v[26:29], v[156:159], v[212:215], v[26:29]
	v_mfma_f32_16x16x32_bf16 v[38:41], v[148:151], v[212:215], v[38:41]
	s_setprio 0
	s_setprio 1
	v_mfma_f32_16x16x32_bf16 v[126:129], v[160:163], v[176:179], v[126:129]
	v_mfma_f32_16x16x32_bf16 v[118:121], v[168:171], v[176:179], v[118:121]
	v_mfma_f32_16x16x32_bf16 v[90:93], v[168:171], v[188:191], v[90:93]
	v_mfma_f32_16x16x32_bf16 v[94:97], v[160:163], v[188:191], v[94:97]
	v_mfma_f32_16x16x32_bf16 v[54:57], v[160:163], v[196:199], v[54:57]
	v_mfma_f32_16x16x32_bf16 v[50:53], v[168:171], v[196:199], v[50:53]
	v_mfma_f32_16x16x32_bf16 v[18:21], v[168:171], v[204:207], v[18:21]
	v_mfma_f32_16x16x32_bf16 v[22:25], v[160:163], v[204:207], v[22:25]
	v_mfma_f32_16x16x32_bf16 v[126:129], v[164:167], v[184:187], v[126:129]
	v_mfma_f32_16x16x32_bf16 v[118:121], v[172:175], v[184:187], v[118:121]
	v_mfma_f32_16x16x32_bf16 v[90:93], v[172:175], v[192:195], v[90:93]
	v_mfma_f32_16x16x32_bf16 v[94:97], v[164:167], v[192:195], v[94:97]
	v_mfma_f32_16x16x32_bf16 v[54:57], v[164:167], v[200:203], v[54:57]
	v_mfma_f32_16x16x32_bf16 v[50:53], v[172:175], v[200:203], v[50:53]
	v_mfma_f32_16x16x32_bf16 v[18:21], v[172:175], v[212:215], v[18:21]
	v_mfma_f32_16x16x32_bf16 v[22:25], v[164:167], v[212:215], v[22:25]
	s_setprio 0
	s_barrier
	ds_read_b128 v[176:179], v140 offset:16384
	ds_read_b128 v[184:187], v140 offset:17408
	ds_read_b128 v[188:191], v140 offset:18432
	ds_read_b128 v[192:195], v140 offset:19456
	ds_read_b128 v[196:199], v140 offset:20480
	ds_read_b128 v[200:203], v140 offset:21504
	ds_read_b128 v[204:207], v140 offset:22528
	ds_read_b128 v[212:215], v140 offset:23552
	s_mov_b32 m0, s57
	s_nop 0
	global_load_lds_dwordx4 v133, s[52:53]
	s_add_u32 s46, s52, 0x80000
	s_mov_b32 m0, s58
	s_nop 0
	global_load_lds_dwordx4 v135, s[52:53]
	s_addc_u32 s47, s53, 0
	s_mov_b32 m0, s59
	s_nop 0
	global_load_lds_dwordx4 v133, s[46:47]
	s_nop 0
	s_mov_b32 m0, s60
	s_nop 0
	global_load_lds_dwordx4 v135, s[46:47]
	s_nop 0
	s_waitcnt vmcnt(6)
	s_waitcnt lgkmcnt(0)
	s_barrier
; #define PG8_STAGE(bufoff, gbase, voff) do { _Pragma("unroll") for (int _i = 0; _i < 2; ++_i) \
;         asm volatile("s_mov_b32 m0, %0\n\ts_nop 0\n\tglobal_load_lds_dwordx4 %1, %2" :: "s"(ldsb + (unsigned)(bufoff) + ldsw + (unsigned)(_i * 8192)), "v"((voff)[_i]), "s"((const char*)(gbase)) : "memory", "m0"); } while (0)
; #define PG8_LDA(dst, b, h) do { _Pragma("unroll") for (int m = 0; m < 4; ++m) _Pragma("unroll") for (int k = 0; k < 2; ++k) dst[m][k] = *(const LAS bf16x8*)(lds + PG8_SA(b, h) + aoff + m * 2048 + k * 1024); } while (0)
; #define PG8_LDB(dst, b, h) do { _Pragma("unroll") for (int n = 0; n < 2; ++n) _Pragma("unroll") for (int k = 0; k < 2; ++k) dst[n][k] = *(const LAS bf16x8*)(lds + PG8_SB(b, h) + boff + n * 2048 + k * 1024); } while (0)
; #define PG8_MMA(ai, bj, At, Bt) do { __builtin_amdgcn_s_setprio(1); _Pragma("unroll") for (int m = 0; m < 4; ++m) _Pragma("unroll") for (int n = 0; n < 2; ++n) _Pragma("unroll") for (int k = 0; k < 2; ++k) \
;         acc[ai][bj][m][n] = __builtin_amdgcn_mfma_f32_16x16x32_bf16(Bt[n][k], At[m][k], acc[ai][bj][m][n], 0, 0, 0); __builtin_amdgcn_s_setprio(0); } while (0)
; #define PG8_WAIT_V(n) asm volatile("s_waitcnt vmcnt(" #n ")" ::: "memory")
; #define PG8_WAIT_L(n) asm volatile("s_waitcnt lgkmcnt(" #n ")" ::: "memory")
; #define PG8_BAR __builtin_amdgcn_s_barrier()
; #define PG8_SCHED __builtin_amdgcn_sched_barrier(0)
; template <class Epi, class Sched>
; __device__ __forceinline__ void gemm_phase(LAS unsigned char* lds, const Gemm g, const Sched& S, const Epi& E) {
;     ...
;             PG8_WAIT_V(8); PG8_WAIT_L(0); PG8_BAR; PG8_MMA(1, 0, At, B0); PG8_MMA(1, 1, At, B1); PG8_BAR; PG8_SCHED;
;             PG8_LDB(B0, 1, 0); PG8_LDB(B1, 1, 1); PG8_SCHED; PG8_LDA(At, 1, 0); PG8_STAGE(PG8_SA(0, 1), a2 + hstepA, voffA);
;             PG8_WAIT_V(8); PG8_WAIT_L(0); PG8_BAR; PG8_MMA(0, 0, At, B0); PG8_MMA(0, 1, At, B1); PG8_BAR; PG8_SCHED;
	s_setprio 1
	s_waitcnt lgkmcnt(7)
	v_mfma_f32_16x16x32_bf16 v[86:89], v[144:147], v[176:179], v[86:89]
	v_mfma_f32_16x16x32_bf16 v[82:85], v[152:155], v[176:179], v[82:85]
	s_waitcnt lgkmcnt(5)
	v_mfma_f32_16x16x32_bf16 v[58:61], v[152:155], v[188:191], v[58:61]
	v_mfma_f32_16x16x32_bf16 v[62:65], v[144:147], v[188:191], v[62:65]
	s_waitcnt lgkmcnt(3)
	v_mfma_f32_16x16x32_bf16 v[34:37], v[144:147], v[196:199], v[34:37]
	v_mfma_f32_16x16x32_bf16 v[30:33], v[152:155], v[196:199], v[30:33]
	s_waitcnt lgkmcnt(1)
	v_mfma_f32_16x16x32_bf16 v[2:5], v[152:155], v[204:207], v[2:5]
	v_mfma_f32_16x16x32_bf16 v[6:9], v[144:147], v[204:207], v[6:9]
	v_mfma_f32_16x16x32_bf16 v[86:89], v[148:151], v[184:187], v[86:89]
	v_mfma_f32_16x16x32_bf16 v[82:85], v[156:159], v[184:187], v[82:85]
	v_mfma_f32_16x16x32_bf16 v[58:61], v[156:159], v[192:195], v[58:61]
	v_mfma_f32_16x16x32_bf16 v[62:65], v[148:151], v[192:195], v[62:65]
	v_mfma_f32_16x16x32_bf16 v[34:37], v[148:151], v[200:203], v[34:37]
	v_mfma_f32_16x16x32_bf16 v[30:33], v[156:159], v[200:203], v[30:33]
	s_waitcnt lgkmcnt(0)
	v_mfma_f32_16x16x32_bf16 v[2:5], v[156:159], v[212:215], v[2:5]
	v_mfma_f32_16x16x32_bf16 v[6:9], v[148:151], v[212:215], v[6:9]
	s_setprio 0
	s_setprio 1
	v_mfma_f32_16x16x32_bf16 v[102:105], v[160:163], v[176:179], v[102:105]
	v_mfma_f32_16x16x32_bf16 v[98:101], v[168:171], v[176:179], v[98:101]
	v_mfma_f32_16x16x32_bf16 v[70:73], v[168:171], v[188:191], v[70:73]
	v_mfma_f32_16x16x32_bf16 v[74:77], v[160:163], v[188:191], v[74:77]
	v_mfma_f32_16x16x32_bf16 v[46:49], v[160:163], v[196:199], v[46:49]
	v_mfma_f32_16x16x32_bf16 v[42:45], v[168:171], v[196:199], v[42:45]
	v_mfma_f32_16x16x32_bf16 v[10:13], v[168:171], v[204:207], v[10:13]
	v_mfma_f32_16x16x32_bf16 v[14:17], v[160:163], v[204:207], v[14:17]
	v_mfma_f32_16x16x32_bf16 v[102:105], v[164:167], v[184:187], v[102:105]
	v_mfma_f32_16x16x32_bf16 v[98:101], v[172:175], v[184:187], v[98:101]
	v_mfma_f32_16x16x32_bf16 v[70:73], v[172:175], v[192:195], v[70:73]
	v_mfma_f32_16x16x32_bf16 v[74:77], v[164:167], v[192:195], v[74:77]
	v_mfma_f32_16x16x32_bf16 v[46:49], v[164:167], v[200:203], v[46:49]
	v_mfma_f32_16x16x32_bf16 v[42:45], v[172:175], v[200:203], v[42:45]
	v_mfma_f32_16x16x32_bf16 v[10:13], v[172:175], v[212:215], v[10:13]
	v_mfma_f32_16x16x32_bf16 v[14:17], v[164:167], v[212:215], v[14:17]
	s_setprio 0
	s_barrier
	ds_read_b128 v[144:147], v141
	ds_read_b128 v[148:151], v141 offset:1024
	ds_read_b128 v[152:155], v141 offset:2048
	ds_read_b128 v[156:159], v141 offset:3072
	ds_read_b128 v[160:163], v142
	ds_read_b128 v[164:167], v142 offset:1024
	ds_read_b128 v[168:171], v142 offset:2048
	ds_read_b128 v[172:175], v142 offset:3072
	ds_read_b128 v[176:179], v140 offset:32768
	ds_read_b128 v[184:187], v140 offset:33792
	ds_read_b128 v[188:191], v140 offset:34816
	ds_read_b128 v[192:195], v140 offset:35840
	ds_read_b128 v[196:199], v140 offset:36864
	ds_read_b128 v[200:203], v140 offset:37888
	ds_read_b128 v[204:207], v140 offset:38912
	ds_read_b128 v[212:215], v140 offset:39936
	s_mov_b32 m0, s56
	s_nop 0
	global_load_lds_dwordx4 v132, s[54:55]
	s_mov_b32 m0, s61
	s_nop 0
	global_load_lds_dwordx4 v134, s[54:55]
	s_add_u32 s46, s54, 0x80000
	s_addc_u32 s47, s55, 0
	s_mov_b32 m0, s62
	s_nop 0
	global_load_lds_dwordx4 v132, s[46:47]
	s_nop 0
	s_mov_b32 m0, s63
	s_nop 0
	global_load_lds_dwordx4 v134, s[46:47]
	s_waitcnt vmcnt(8)
	s_waitcnt lgkmcnt(0)
	s_barrier
; #define PG8_STAGE(bufoff, gbase, voff) do { _Pragma("unroll") for (int _i = 0; _i < 2; ++_i) \
;         asm volatile("s_mov_b32 m0, %0\n\ts_nop 0\n\tglobal_load_lds_dwordx4 %1, %2" :: "s"(ldsb + (unsigned)(bufoff) + ldsw + (unsigned)(_i * 8192)), "v"((voff)[_i]), "s"((const char*)(gbase)) : "memory", "m0"); } while (0)
; #define PG8_LDA(dst, b, h) do { _Pragma("unroll") for (int m = 0; m < 4; ++m) _Pragma("unroll") for (int k = 0; k < 2; ++k) dst[m][k] = *(const LAS bf16x8*)(lds + PG8_SA(b, h) + aoff + m * 2048 + k * 1024); } while (0)
; #define PG8_MMA(ai, bj, At, Bt) do { __builtin_amdgcn_s_setprio(1); _Pragma("unroll") for (int m = 0; m < 4; ++m) _Pragma("unroll") for (int n = 0; n < 2; ++n) _Pragma("unroll") for (int k = 0; k < 2; ++k) \
;         acc[ai][bj][m][n] = __builtin_amdgcn_mfma_f32_16x16x32_bf16(Bt[n][k], At[m][k], acc[ai][bj][m][n], 0, 0, 0); __builtin_amdgcn_s_setprio(0); } while (0)
; #define PG8_WAIT_V(n) asm volatile("s_waitcnt vmcnt(" #n ")" ::: "memory")
; #define PG8_WAIT_L(n) asm volatile("s_waitcnt lgkmcnt(" #n ")" ::: "memory")
; #define PG8_BAR __builtin_amdgcn_s_barrier()
; #define PG8_SCHED __builtin_amdgcn_sched_barrier(0)
; template <class Epi, class Sched>
; __device__ __forceinline__ void gemm_phase(LAS unsigned char* lds, const Gemm g, const Sched& S, const Epi& E) {
;     ...
;             PG8_WAIT_V(8); PG8_WAIT_L(0); PG8_BAR; PG8_MMA(0, 0, At, B0); PG8_MMA(0, 1, At, B1); PG8_BAR; PG8_SCHED;
;             PG8_LDA(At, 1, 1); PG8_STAGE(PG8_SB(1, 0), b3, voffB); PG8_STAGE(PG8_SB(1, 1), b3 + hstepB, voffB); PG8_STAGE(PG8_SA(1, 0), a3, voffA);
;             PG8_WAIT_V(8); PG8_WAIT_L(0); PG8_BAR; PG8_MMA(1, 0, At, B0); PG8_MMA(1, 1, At, B1); PG8_BAR; PG8_SCHED;
;         }
	s_setprio 1
	s_waitcnt lgkmcnt(7)
	v_mfma_f32_16x16x32_bf16 v[122:125], v[144:147], v[176:179], v[122:125]
	v_mfma_f32_16x16x32_bf16 v[114:117], v[152:155], v[176:179], v[114:117]
	s_waitcnt lgkmcnt(5)
	v_mfma_f32_16x16x32_bf16 v[106:109], v[152:155], v[188:191], v[106:109]
	v_mfma_f32_16x16x32_bf16 v[110:113], v[144:147], v[188:191], v[110:113]
	s_waitcnt lgkmcnt(3)
	v_mfma_f32_16x16x32_bf16 v[78:81], v[144:147], v[196:199], v[78:81]
	v_mfma_f32_16x16x32_bf16 v[66:69], v[152:155], v[196:199], v[66:69]
	s_waitcnt lgkmcnt(1)
	v_mfma_f32_16x16x32_bf16 v[26:29], v[152:155], v[204:207], v[26:29]
	v_mfma_f32_16x16x32_bf16 v[38:41], v[144:147], v[204:207], v[38:41]
	v_mfma_f32_16x16x32_bf16 v[122:125], v[148:151], v[184:187], v[122:125]
	v_mfma_f32_16x16x32_bf16 v[114:117], v[156:159], v[184:187], v[114:117]
	v_mfma_f32_16x16x32_bf16 v[106:109], v[156:159], v[192:195], v[106:109]
	v_mfma_f32_16x16x32_bf16 v[110:113], v[148:151], v[192:195], v[110:113]
	v_mfma_f32_16x16x32_bf16 v[78:81], v[148:151], v[200:203], v[78:81]
	v_mfma_f32_16x16x32_bf16 v[66:69], v[156:159], v[200:203], v[66:69]
	s_waitcnt lgkmcnt(0)
	v_mfma_f32_16x16x32_bf16 v[26:29], v[156:159], v[212:215], v[26:29]
	v_mfma_f32_16x16x32_bf16 v[38:41], v[148:151], v[212:215], v[38:41]
	s_setprio 0
	s_setprio 1
	v_mfma_f32_16x16x32_bf16 v[126:129], v[160:163], v[176:179], v[126:129]
	v_mfma_f32_16x16x32_bf16 v[118:121], v[168:171], v[176:179], v[118:121]
	v_mfma_f32_16x16x32_bf16 v[90:93], v[168:171], v[188:191], v[90:93]
	v_mfma_f32_16x16x32_bf16 v[94:97], v[160:163], v[188:191], v[94:97]
	v_mfma_f32_16x16x32_bf16 v[54:57], v[160:163], v[196:199], v[54:57]
	v_mfma_f32_16x16x32_bf16 v[50:53], v[168:171], v[196:199], v[50:53]
	v_mfma_f32_16x16x32_bf16 v[18:21], v[168:171], v[204:207], v[18:21]
	v_mfma_f32_16x16x32_bf16 v[22:25], v[160:163], v[204:207], v[22:25]
	v_mfma_f32_16x16x32_bf16 v[126:129], v[164:167], v[184:187], v[126:129]
	v_mfma_f32_16x16x32_bf16 v[118:121], v[172:175], v[184:187], v[118:121]
	v_mfma_f32_16x16x32_bf16 v[90:93], v[172:175], v[192:195], v[90:93]
	v_mfma_f32_16x16x32_bf16 v[94:97], v[164:167], v[192:195], v[94:97]
	v_mfma_f32_16x16x32_bf16 v[54:57], v[164:167], v[200:203], v[54:57]
	v_mfma_f32_16x16x32_bf16 v[50:53], v[172:175], v[200:203], v[50:53]
	v_mfma_f32_16x16x32_bf16 v[18:21], v[172:175], v[212:215], v[18:21]
	v_mfma_f32_16x16x32_bf16 v[22:25], v[164:167], v[212:215], v[22:25]
	s_setprio 0
	s_barrier
	ds_read_b128 v[176:179], v140 offset:49152
	ds_read_b128 v[184:187], v140 offset:50176
	ds_read_b128 v[188:191], v140 offset:51200
	ds_read_b128 v[192:195], v140 offset:52224
	ds_read_b128 v[196:199], v140 offset:53248
	ds_read_b128 v[200:203], v140 offset:54272
	ds_read_b128 v[204:207], v140 offset:55296
	ds_read_b128 v[212:215], v140 offset:56320
	s_add_u32 s46, s52, 0x80
	s_addc_u32 s47, s53, 0
	s_mov_b32 m0, s64
	s_nop 0
	global_load_lds_dwordx4 v133, s[46:47]
	s_nop 0
	s_mov_b32 m0, s65
	s_nop 0
	global_load_lds_dwordx4 v135, s[46:47]
	s_add_u32 s46, s52, 0x80080
	s_addc_u32 s47, s53, 0
	s_mov_b32 m0, s68
	s_nop 0
	global_load_lds_dwordx4 v133, s[46:47]
	s_nop 0
	s_mov_b32 m0, s69
	s_nop 0
	global_load_lds_dwordx4 v135, s[46:47]
	s_nop 0
	s_waitcnt vmcnt(6)
	s_waitcnt lgkmcnt(0)
	s_barrier
	s_setprio 1
	s_waitcnt lgkmcnt(7)
	v_mfma_f32_16x16x32_bf16 v[86:89], v[144:147], v[176:179], v[86:89]
	v_mfma_f32_16x16x32_bf16 v[82:85], v[152:155], v[176:179], v[82:85]
	s_waitcnt lgkmcnt(5)
	v_mfma_f32_16x16x32_bf16 v[58:61], v[152:155], v[188:191], v[58:61]
	v_mfma_f32_16x16x32_bf16 v[62:65], v[144:147], v[188:191], v[62:65]
	s_waitcnt lgkmcnt(3)
	v_mfma_f32_16x16x32_bf16 v[34:37], v[144:147], v[196:199], v[34:37]
	v_mfma_f32_16x16x32_bf16 v[30:33], v[152:155], v[196:199], v[30:33]
	s_waitcnt lgkmcnt(1)
	v_mfma_f32_16x16x32_bf16 v[2:5], v[152:155], v[204:207], v[2:5]
	v_mfma_f32_16x16x32_bf16 v[6:9], v[144:147], v[204:207], v[6:9]
	v_mfma_f32_16x16x32_bf16 v[86:89], v[148:151], v[184:187], v[86:89]
	v_mfma_f32_16x16x32_bf16 v[82:85], v[156:159], v[184:187], v[82:85]
	v_mfma_f32_16x16x32_bf16 v[58:61], v[156:159], v[192:195], v[58:61]
	v_mfma_f32_16x16x32_bf16 v[62:65], v[148:151], v[192:195], v[62:65]
	v_mfma_f32_16x16x32_bf16 v[34:37], v[148:151], v[200:203], v[34:37]
	v_mfma_f32_16x16x32_bf16 v[30:33], v[156:159], v[200:203], v[30:33]
	s_waitcnt lgkmcnt(0)
	v_mfma_f32_16x16x32_bf16 v[2:5], v[156:159], v[212:215], v[2:5]
	v_mfma_f32_16x16x32_bf16 v[6:9], v[148:151], v[212:215], v[6:9]
	s_setprio 0
	s_setprio 1
	v_mfma_f32_16x16x32_bf16 v[102:105], v[160:163], v[176:179], v[102:105]
	v_mfma_f32_16x16x32_bf16 v[98:101], v[168:171], v[176:179], v[98:101]
	v_mfma_f32_16x16x32_bf16 v[70:73], v[168:171], v[188:191], v[70:73]
	v_mfma_f32_16x16x32_bf16 v[74:77], v[160:163], v[188:191], v[74:77]
	v_mfma_f32_16x16x32_bf16 v[46:49], v[160:163], v[196:199], v[46:49]
	v_mfma_f32_16x16x32_bf16 v[42:45], v[168:171], v[196:199], v[42:45]
	v_mfma_f32_16x16x32_bf16 v[10:13], v[168:171], v[204:207], v[10:13]
	v_mfma_f32_16x16x32_bf16 v[14:17], v[160:163], v[204:207], v[14:17]
	v_mfma_f32_16x16x32_bf16 v[102:105], v[164:167], v[184:187], v[102:105]
	v_mfma_f32_16x16x32_bf16 v[98:101], v[172:175], v[184:187], v[98:101]
	v_mfma_f32_16x16x32_bf16 v[70:73], v[172:175], v[192:195], v[70:73]
	v_mfma_f32_16x16x32_bf16 v[74:77], v[164:167], v[192:195], v[74:77]
	v_mfma_f32_16x16x32_bf16 v[46:49], v[164:167], v[200:203], v[46:49]
	v_mfma_f32_16x16x32_bf16 v[42:45], v[172:175], v[200:203], v[42:45]
	v_mfma_f32_16x16x32_bf16 v[10:13], v[172:175], v[212:215], v[10:13]
	v_mfma_f32_16x16x32_bf16 v[14:17], v[164:167], v[212:215], v[14:17]
	s_setprio 0
	s_barrier
	s_add_i32 s42, s42, 2
	s_add_u32 s38, s38, 0x100
	s_addc_u32 s39, s39, 0
	s_add_u32 s40, s40, 0x100
	s_addc_u32 s41, s41, 0
	s_cmp_gt_u32 s42, 29
	s_cbranch_scc0 .LBB0_168

; #define PG8_STAGE(bufoff, gbase, voff) do { _Pragma("unroll") for (int _i = 0; _i < 2; ++_i) \
;         asm volatile("s_mov_b32 m0, %0\n\ts_nop 0\n\tglobal_load_lds_dwordx4 %1, %2" :: "s"(ldsb + (unsigned)(bufoff) + ldsw + (unsigned)(_i * 8192)), "v"((voff)[_i]), "s"((const char*)(gbase)) : "memory", "m0"); } while (0)
; #define PG8_LDA(dst, b, h) do { _Pragma("unroll") for (int m = 0; m < 4; ++m) _Pragma("unroll") for (int k = 0; k < 2; ++k) dst[m][k] = *(const LAS bf16x8*)(lds + PG8_SA(b, h) + aoff + m * 2048 + k * 1024); } while (0)
; #define PG8_LDB(dst, b, h) do { _Pragma("unroll") for (int n = 0; n < 2; ++n) _Pragma("unroll") for (int k = 0; k < 2; ++k) dst[n][k] = *(const LAS bf16x8*)(lds + PG8_SB(b, h) + boff + n * 2048 + k * 1024); } while (0)
; #define PG8_MMA(ai, bj, At, Bt) do { __builtin_amdgcn_s_setprio(1); _Pragma("unroll") for (int m = 0; m < 4; ++m) _Pragma("unroll") for (int n = 0; n < 2; ++n) _Pragma("unroll") for (int k = 0; k < 2; ++k) \
;         acc[ai][bj][m][n] = __builtin_amdgcn_mfma_f32_16x16x32_bf16(Bt[n][k], At[m][k], acc[ai][bj][m][n], 0, 0, 0); __builtin_amdgcn_s_setprio(0); } while (0)
; #define PG8_WAIT_V(n) asm volatile("s_waitcnt vmcnt(" #n ")" ::: "memory")
; template <class Epi, class Sched>
; __device__ __forceinline__ void gemm_phase(LAS unsigned char* lds, const Gemm g, const Sched& S, const Epi& E) {
;     ...
;             PG8_LDB(B0, 0, 0); PG8_LDB(B1, 0, 1); PG8_SCHED; PG8_LDA(At, 0, 0); PG8_STAGE(PG8_SA(1, 1), a1 + hstepA, voffA);
;             PG8_WAIT_V(8); PG8_WAIT_L(0); PG8_BAR; PG8_MMA(0, 0, At, B0); PG8_MMA(0, 1, At, B1); PG8_BAR; PG8_SCHED;
;             PG8_LDA(At, 0, 1); PG8_STAGE(PG8_SB(0, 0), b2, voffB); PG8_STAGE(PG8_SB(0, 1), b2 + hstepB, voffB); PG8_STAGE(PG8_SA(0, 0), a2, voffA);
;             PG8_WAIT_V(8); PG8_WAIT_L(0); PG8_BAR; PG8_MMA(1, 0, At, B0); PG8_MMA(1, 1, At, B1); PG8_BAR; PG8_SCHED;
;             PG8_LDB(B0, 1, 0); PG8_LDB(B1, 1, 1); PG8_SCHED; PG8_LDA(At, 1, 0); PG8_STAGE(PG8_SA(0, 1), a2 + hstepA, voffA);
;             PG8_WAIT_V(8); PG8_WAIT_L(0); PG8_BAR; PG8_MMA(0, 0, At, B0); PG8_MMA(0, 1, At, B1); PG8_BAR; PG8_SCHED;
;             PG8_LDA(At, 1, 1); PG8_STAGE(PG8_SB(1, 0), b3, voffB); PG8_STAGE(PG8_SB(1, 1), b3 + hstepB, voffB); PG8_STAGE(PG8_SA(1, 0), a3, voffA);
;             PG8_WAIT_V(8); PG8_WAIT_L(0); PG8_BAR; PG8_MMA(1, 0, At, B0); PG8_MMA(1, 1, At, B1); PG8_BAR; PG8_SCHED;
.LBB0_1010:
	s_or_b32 s4, s65, 1
	s_lshl_b64 s[66:67], s[4:5], 7
	s_add_i32 s4, s65, 2
	s_lshl_b64 s[42:43], s[4:5], 7
	s_add_u32 s68, s30, s42
	v_add_u32_e32 v141, 0, v137
	s_addc_u32 s69, s31, s43
	v_add_u32_e32 v154, 0x10000, v141
	v_add_u32_e32 v170, 0x14000, v141
	s_and_b64 s[44:45], s[40:41], exec
	ds_read_b128 v[142:145], v154
	ds_read_b128 v[146:149], v154 offset:1024
	ds_read_b128 v[150:153], v154 offset:2048
	ds_read_b128 v[154:157], v154 offset:3072
	ds_read_b128 v[158:161], v170
	ds_read_b128 v[162:165], v170 offset:1024
	ds_read_b128 v[166:169], v170 offset:2048
	ds_read_b128 v[170:173], v170 offset:3072
	s_cselect_b32 s45, s13, s69
	s_cselect_b32 s44, s21, s68
	s_add_u32 s68, s36, s42
	s_addc_u32 s69, s37, s43
	s_add_u32 s42, s44, 0x80
	s_addc_u32 s43, s45, 0
	s_and_b64 s[40:41], s[40:41], exec
	s_cselect_b32 s41, s15, s69
	s_cselect_b32 s40, s64, s68
	s_add_u32 s66, s30, s66
	s_addc_u32 s67, s31, s67
	v_add_u32_e32 v206, 0, v136
	ds_read_b128 v[174:177], v206
	ds_read_b128 v[178:181], v206 offset:1024
	ds_read_b128 v[182:185], v206 offset:2048
	ds_read_b128 v[186:189], v206 offset:3072
	ds_read_b128 v[190:193], v206 offset:4096
	ds_read_b128 v[194:197], v206 offset:5120
	ds_read_b128 v[198:201], v206 offset:6144
	ds_read_b128 v[202:205], v206 offset:7168
	s_mov_b32 m0, s55
	s_nop 0
	global_load_lds_dwordx4 v1, s[66:67]
	s_mov_b32 m0, s56
	s_nop 0
	global_load_lds_dwordx4 v133, s[66:67]
	s_add_u32 s66, s66, 0x80000
	s_addc_u32 s67, s67, 0
	s_mov_b32 m0, s59
	s_nop 0
	global_load_lds_dwordx4 v1, s[66:67]
	s_nop 0
	s_mov_b32 m0, s60
	s_nop 0
	global_load_lds_dwordx4 v133, s[66:67]
	s_waitcnt vmcnt(8)
	s_waitcnt lgkmcnt(0)
	s_barrier
	s_setprio 1
	s_waitcnt lgkmcnt(7)
	v_mfma_f32_16x16x32_bf16 v[122:125], v[142:145], v[174:177], v[122:125]
	v_mfma_f32_16x16x32_bf16 v[114:117], v[150:153], v[174:177], v[114:117]
	s_waitcnt lgkmcnt(5)
	v_mfma_f32_16x16x32_bf16 v[86:89], v[150:153], v[182:185], v[86:89]
	v_mfma_f32_16x16x32_bf16 v[94:97], v[142:145], v[182:185], v[94:97]
	s_waitcnt lgkmcnt(3)
	v_mfma_f32_16x16x32_bf16 v[54:57], v[142:145], v[190:193], v[54:57]
	v_mfma_f32_16x16x32_bf16 v[50:53], v[150:153], v[190:193], v[50:53]
	s_waitcnt lgkmcnt(1)
	v_mfma_f32_16x16x32_bf16 v[10:13], v[150:153], v[198:201], v[10:13]
	v_mfma_f32_16x16x32_bf16 v[14:17], v[142:145], v[198:201], v[14:17]
	v_mfma_f32_16x16x32_bf16 v[122:125], v[146:149], v[178:181], v[122:125]
	v_mfma_f32_16x16x32_bf16 v[114:117], v[154:157], v[178:181], v[114:117]
	v_mfma_f32_16x16x32_bf16 v[86:89], v[154:157], v[186:189], v[86:89]
	v_mfma_f32_16x16x32_bf16 v[94:97], v[146:149], v[186:189], v[94:97]
	v_mfma_f32_16x16x32_bf16 v[54:57], v[146:149], v[194:197], v[54:57]
	v_mfma_f32_16x16x32_bf16 v[50:53], v[154:157], v[194:197], v[50:53]
	s_waitcnt lgkmcnt(0)
	v_mfma_f32_16x16x32_bf16 v[10:13], v[154:157], v[202:205], v[10:13]
	v_mfma_f32_16x16x32_bf16 v[14:17], v[146:149], v[202:205], v[14:17]
	s_setprio 0
	s_setprio 1
	v_mfma_f32_16x16x32_bf16 v[126:129], v[158:161], v[174:177], v[126:129]
	v_mfma_f32_16x16x32_bf16 v[118:121], v[166:169], v[174:177], v[118:121]
	v_mfma_f32_16x16x32_bf16 v[66:69], v[166:169], v[182:185], v[66:69]
	v_mfma_f32_16x16x32_bf16 v[70:73], v[158:161], v[182:185], v[70:73]
	v_mfma_f32_16x16x32_bf16 v[38:41], v[158:161], v[190:193], v[38:41]
	v_mfma_f32_16x16x32_bf16 v[34:37], v[166:169], v[190:193], v[34:37]
	v_mfma_f32_16x16x32_bf16 v[2:5], v[166:169], v[198:201], v[2:5]
	v_mfma_f32_16x16x32_bf16 v[6:9], v[158:161], v[198:201], v[6:9]
	v_mfma_f32_16x16x32_bf16 v[126:129], v[162:165], v[178:181], v[126:129]
	v_mfma_f32_16x16x32_bf16 v[118:121], v[170:173], v[178:181], v[118:121]
	v_mfma_f32_16x16x32_bf16 v[66:69], v[170:173], v[186:189], v[66:69]
	v_mfma_f32_16x16x32_bf16 v[70:73], v[162:165], v[186:189], v[70:73]
	v_mfma_f32_16x16x32_bf16 v[38:41], v[162:165], v[194:197], v[38:41]
	v_mfma_f32_16x16x32_bf16 v[34:37], v[170:173], v[194:197], v[34:37]
	v_mfma_f32_16x16x32_bf16 v[2:5], v[170:173], v[202:205], v[2:5]
	v_mfma_f32_16x16x32_bf16 v[6:9], v[162:165], v[202:205], v[6:9]
	s_setprio 0
	s_barrier
	ds_read_b128 v[174:177], v206 offset:16384
	ds_read_b128 v[178:181], v206 offset:17408
	ds_read_b128 v[182:185], v206 offset:18432
	ds_read_b128 v[186:189], v206 offset:19456
	ds_read_b128 v[190:193], v206 offset:20480
	ds_read_b128 v[194:197], v206 offset:21504
	ds_read_b128 v[198:201], v206 offset:22528
	ds_read_b128 v[202:205], v206 offset:23552
	s_mov_b32 m0, s46
	s_nop 0
	global_load_lds_dwordx4 v132, s[40:41]
	s_add_u32 s66, s40, 0x80000
	s_mov_b32 m0, s47
	s_nop 0
	global_load_lds_dwordx4 v134, s[40:41]
	s_addc_u32 s67, s41, 0
	s_mov_b32 m0, s48
	s_nop 0
	global_load_lds_dwordx4 v132, s[66:67]
	s_nop 0
	s_mov_b32 m0, s49
	s_nop 0
	global_load_lds_dwordx4 v134, s[66:67]
	s_nop 0
	s_waitcnt vmcnt(6)
	s_waitcnt lgkmcnt(0)
	s_barrier
; #define PG8_STAGE(bufoff, gbase, voff) do { _Pragma("unroll") for (int _i = 0; _i < 2; ++_i) \
;         asm volatile("s_mov_b32 m0, %0\n\ts_nop 0\n\tglobal_load_lds_dwordx4 %1, %2" :: "s"(ldsb + (unsigned)(bufoff) + ldsw + (unsigned)(_i * 8192)), "v"((voff)[_i]), "s"((const char*)(gbase)) : "memory", "m0"); } while (0)
; #define PG8_LDA(dst, b, h) do { _Pragma("unroll") for (int m = 0; m < 4; ++m) _Pragma("unroll") for (int k = 0; k < 2; ++k) dst[m][k] = *(const LAS bf16x8*)(lds + PG8_SA(b, h) + aoff + m * 2048 + k * 1024); } while (0)
; #define PG8_LDB(dst, b, h) do { _Pragma("unroll") for (int n = 0; n < 2; ++n) _Pragma("unroll") for (int k = 0; k < 2; ++k) dst[n][k] = *(const LAS bf16x8*)(lds + PG8_SB(b, h) + boff + n * 2048 + k * 1024); } while (0)
; #define PG8_MMA(ai, bj, At, Bt) do { __builtin_amdgcn_s_setprio(1); _Pragma("unroll") for (int m = 0; m < 4; ++m) _Pragma("unroll") for (int n = 0; n < 2; ++n) _Pragma("unroll") for (int k = 0; k < 2; ++k) \
;         acc[ai][bj][m][n] = __builtin_amdgcn_mfma_f32_16x16x32_bf16(Bt[n][k], At[m][k], acc[ai][bj][m][n], 0, 0, 0); __builtin_amdgcn_s_setprio(0); } while (0)
; #define PG8_WAIT_V(n) asm volatile("s_waitcnt vmcnt(" #n ")" ::: "memory")
; #define PG8_WAIT_L(n) asm volatile("s_waitcnt lgkmcnt(" #n ")" ::: "memory")
; #define PG8_BAR __builtin_amdgcn_s_barrier()
; #define PG8_SCHED __builtin_amdgcn_sched_barrier(0)
; template <class Epi, class Sched>
; __device__ __forceinline__ void gemm_phase(LAS unsigned char* lds, const Gemm g, const Sched& S, const Epi& E) {
;     ...
;             PG8_WAIT_V(8); PG8_WAIT_L(0); PG8_BAR; PG8_MMA(1, 0, At, B0); PG8_MMA(1, 1, At, B1); PG8_BAR; PG8_SCHED;
;             PG8_LDB(B0, 1, 0); PG8_LDB(B1, 1, 1); PG8_SCHED; PG8_LDA(At, 1, 0); PG8_STAGE(PG8_SA(0, 1), a2 + hstepA, voffA);
;             PG8_WAIT_V(8); PG8_WAIT_L(0); PG8_BAR; PG8_MMA(0, 0, At, B0); PG8_MMA(0, 1, At, B1); PG8_BAR; PG8_SCHED;
	s_setprio 1
	s_waitcnt lgkmcnt(7)
	v_mfma_f32_16x16x32_bf16 v[102:105], v[142:145], v[174:177], v[102:105]
	v_mfma_f32_16x16x32_bf16 v[98:101], v[150:153], v[174:177], v[98:101]
	s_waitcnt lgkmcnt(5)
	v_mfma_f32_16x16x32_bf16 v[74:77], v[150:153], v[182:185], v[74:77]
	v_mfma_f32_16x16x32_bf16 v[78:81], v[142:145], v[182:185], v[78:81]
	s_waitcnt lgkmcnt(3)
	v_mfma_f32_16x16x32_bf16 v[46:49], v[142:145], v[190:193], v[46:49]
	v_mfma_f32_16x16x32_bf16 v[42:45], v[150:153], v[190:193], v[42:45]
	s_waitcnt lgkmcnt(1)
	v_mfma_f32_16x16x32_bf16 v[18:21], v[150:153], v[198:201], v[18:21]
	v_mfma_f32_16x16x32_bf16 v[22:25], v[142:145], v[198:201], v[22:25]
	v_mfma_f32_16x16x32_bf16 v[102:105], v[146:149], v[178:181], v[102:105]
	v_mfma_f32_16x16x32_bf16 v[98:101], v[154:157], v[178:181], v[98:101]
	v_mfma_f32_16x16x32_bf16 v[74:77], v[154:157], v[186:189], v[74:77]
	v_mfma_f32_16x16x32_bf16 v[78:81], v[146:149], v[186:189], v[78:81]
	v_mfma_f32_16x16x32_bf16 v[46:49], v[146:149], v[194:197], v[46:49]
	v_mfma_f32_16x16x32_bf16 v[42:45], v[154:157], v[194:197], v[42:45]
	s_waitcnt lgkmcnt(0)
	v_mfma_f32_16x16x32_bf16 v[18:21], v[154:157], v[202:205], v[18:21]
	v_mfma_f32_16x16x32_bf16 v[22:25], v[146:149], v[202:205], v[22:25]
	s_setprio 0
	s_setprio 1
	v_mfma_f32_16x16x32_bf16 v[110:113], v[158:161], v[174:177], v[110:113]
	v_mfma_f32_16x16x32_bf16 v[106:109], v[166:169], v[174:177], v[106:109]
	v_mfma_f32_16x16x32_bf16 v[82:85], v[166:169], v[182:185], v[82:85]
	v_mfma_f32_16x16x32_bf16 v[90:93], v[158:161], v[182:185], v[90:93]
	v_mfma_f32_16x16x32_bf16 v[62:65], v[158:161], v[190:193], v[62:65]
	v_mfma_f32_16x16x32_bf16 v[58:61], v[166:169], v[190:193], v[58:61]
	v_mfma_f32_16x16x32_bf16 v[26:29], v[166:169], v[198:201], v[26:29]
	v_mfma_f32_16x16x32_bf16 v[30:33], v[158:161], v[198:201], v[30:33]
	v_mfma_f32_16x16x32_bf16 v[110:113], v[162:165], v[178:181], v[110:113]
	v_mfma_f32_16x16x32_bf16 v[106:109], v[170:173], v[178:181], v[106:109]
	v_mfma_f32_16x16x32_bf16 v[82:85], v[170:173], v[186:189], v[82:85]
	v_mfma_f32_16x16x32_bf16 v[90:93], v[162:165], v[186:189], v[90:93]
	v_mfma_f32_16x16x32_bf16 v[62:65], v[162:165], v[194:197], v[62:65]
	v_mfma_f32_16x16x32_bf16 v[58:61], v[170:173], v[194:197], v[58:61]
	v_mfma_f32_16x16x32_bf16 v[26:29], v[170:173], v[202:205], v[26:29]
	v_mfma_f32_16x16x32_bf16 v[30:33], v[162:165], v[202:205], v[30:33]
	s_setprio 0
	s_barrier
	v_add_u32_e32 v154, 0x18000, v141
	v_add_u32_e32 v141, 0x1c000, v141
	ds_read_b128 v[142:145], v154
	ds_read_b128 v[146:149], v154 offset:1024
	ds_read_b128 v[150:153], v154 offset:2048
	ds_read_b128 v[154:157], v154 offset:3072
	ds_read_b128 v[158:161], v141
	ds_read_b128 v[162:165], v141 offset:1024
	ds_read_b128 v[166:169], v141 offset:2048
	ds_read_b128 v[170:173], v141 offset:3072
	ds_read_b128 v[174:177], v206 offset:32768
	ds_read_b128 v[178:181], v206 offset:33792
	ds_read_b128 v[182:185], v206 offset:34816
	ds_read_b128 v[186:189], v206 offset:35840
	ds_read_b128 v[190:193], v206 offset:36864
	ds_read_b128 v[194:197], v206 offset:37888
	ds_read_b128 v[198:201], v206 offset:38912
	ds_read_b128 v[202:205], v206 offset:39936
	s_mov_b32 m0, s35
	s_nop 0
	global_load_lds_dwordx4 v1, s[44:45]
	s_mov_b32 m0, s50
	s_nop 0
	global_load_lds_dwordx4 v133, s[44:45]
	s_add_u32 s44, s44, 0x80000
	s_addc_u32 s45, s45, 0
	s_mov_b32 m0, s51
	s_nop 0
	global_load_lds_dwordx4 v1, s[44:45]
	s_nop 0
	s_mov_b32 m0, s52
	s_nop 0
	global_load_lds_dwordx4 v133, s[44:45]
	s_waitcnt vmcnt(8)
	s_waitcnt lgkmcnt(0)
	s_barrier
; #define PG8_STAGE(bufoff, gbase, voff) do { _Pragma("unroll") for (int _i = 0; _i < 2; ++_i) \
;         asm volatile("s_mov_b32 m0, %0\n\ts_nop 0\n\tglobal_load_lds_dwordx4 %1, %2" :: "s"(ldsb + (unsigned)(bufoff) + ldsw + (unsigned)(_i * 8192)), "v"((voff)[_i]), "s"((const char*)(gbase)) : "memory", "m0"); } while (0)
; #define PG8_LDA(dst, b, h) do { _Pragma("unroll") for (int m = 0; m < 4; ++m) _Pragma("unroll") for (int k = 0; k < 2; ++k) dst[m][k] = *(const LAS bf16x8*)(lds + PG8_SA(b, h) + aoff + m * 2048 + k * 1024); } while (0)
; #define PG8_MMA(ai, bj, At, Bt) do { __builtin_amdgcn_s_setprio(1); _Pragma("unroll") for (int m = 0; m < 4; ++m) _Pragma("unroll") for (int n = 0; n < 2; ++n) _Pragma("unroll") for (int k = 0; k < 2; ++k) \
;         acc[ai][bj][m][n] = __builtin_amdgcn_mfma_f32_16x16x32_bf16(Bt[n][k], At[m][k], acc[ai][bj][m][n], 0, 0, 0); __builtin_amdgcn_s_setprio(0); } while (0)
; #define PG8_WAIT_V(n) asm volatile("s_waitcnt vmcnt(" #n ")" ::: "memory")
; #define PG8_WAIT_L(n) asm volatile("s_waitcnt lgkmcnt(" #n ")" ::: "memory")
; #define PG8_BAR __builtin_amdgcn_s_barrier()
; #define PG8_SCHED __builtin_amdgcn_sched_barrier(0)
; template <class Epi, class Sched>
; __device__ __forceinline__ void gemm_phase(LAS unsigned char* lds, const Gemm g, const Sched& S, const Epi& E) {
;     ...
;             PG8_WAIT_V(8); PG8_WAIT_L(0); PG8_BAR; PG8_MMA(0, 0, At, B0); PG8_MMA(0, 1, At, B1); PG8_BAR; PG8_SCHED;
;             PG8_LDA(At, 1, 1); PG8_STAGE(PG8_SB(1, 0), b3, voffB); PG8_STAGE(PG8_SB(1, 1), b3 + hstepB, voffB); PG8_STAGE(PG8_SA(1, 0), a3, voffA);
;             PG8_WAIT_V(8); PG8_WAIT_L(0); PG8_BAR; PG8_MMA(1, 0, At, B0); PG8_MMA(1, 1, At, B1); PG8_BAR; PG8_SCHED;
;         }
	s_setprio 1
	s_waitcnt lgkmcnt(7)
	v_mfma_f32_16x16x32_bf16 v[122:125], v[142:145], v[174:177], v[122:125]
	v_mfma_f32_16x16x32_bf16 v[114:117], v[150:153], v[174:177], v[114:117]
	s_waitcnt lgkmcnt(5)
	v_mfma_f32_16x16x32_bf16 v[86:89], v[150:153], v[182:185], v[86:89]
	v_mfma_f32_16x16x32_bf16 v[94:97], v[142:145], v[182:185], v[94:97]
	s_waitcnt lgkmcnt(3)
	v_mfma_f32_16x16x32_bf16 v[54:57], v[142:145], v[190:193], v[54:57]
	v_mfma_f32_16x16x32_bf16 v[50:53], v[150:153], v[190:193], v[50:53]
	s_waitcnt lgkmcnt(1)
	v_mfma_f32_16x16x32_bf16 v[10:13], v[150:153], v[198:201], v[10:13]
	v_mfma_f32_16x16x32_bf16 v[14:17], v[142:145], v[198:201], v[14:17]
	v_mfma_f32_16x16x32_bf16 v[122:125], v[146:149], v[178:181], v[122:125]
	v_mfma_f32_16x16x32_bf16 v[114:117], v[154:157], v[178:181], v[114:117]
	v_mfma_f32_16x16x32_bf16 v[86:89], v[154:157], v[186:189], v[86:89]
	v_mfma_f32_16x16x32_bf16 v[94:97], v[146:149], v[186:189], v[94:97]
	v_mfma_f32_16x16x32_bf16 v[54:57], v[146:149], v[194:197], v[54:57]
	v_mfma_f32_16x16x32_bf16 v[50:53], v[154:157], v[194:197], v[50:53]
	s_waitcnt lgkmcnt(0)
	v_mfma_f32_16x16x32_bf16 v[10:13], v[154:157], v[202:205], v[10:13]
	v_mfma_f32_16x16x32_bf16 v[14:17], v[146:149], v[202:205], v[14:17]
	s_setprio 0
	s_setprio 1
	v_mfma_f32_16x16x32_bf16 v[126:129], v[158:161], v[174:177], v[126:129]
	v_mfma_f32_16x16x32_bf16 v[118:121], v[166:169], v[174:177], v[118:121]
	v_mfma_f32_16x16x32_bf16 v[66:69], v[166:169], v[182:185], v[66:69]
	v_mfma_f32_16x16x32_bf16 v[70:73], v[158:161], v[182:185], v[70:73]
	v_mfma_f32_16x16x32_bf16 v[38:41], v[158:161], v[190:193], v[38:41]
	v_mfma_f32_16x16x32_bf16 v[34:37], v[166:169], v[190:193], v[34:37]
	v_mfma_f32_16x16x32_bf16 v[2:5], v[166:169], v[198:201], v[2:5]
	v_mfma_f32_16x16x32_bf16 v[6:9], v[158:161], v[198:201], v[6:9]
	v_mfma_f32_16x16x32_bf16 v[126:129], v[162:165], v[178:181], v[126:129]
	v_mfma_f32_16x16x32_bf16 v[118:121], v[170:173], v[178:181], v[118:121]
	v_mfma_f32_16x16x32_bf16 v[66:69], v[170:173], v[186:189], v[66:69]
	v_mfma_f32_16x16x32_bf16 v[70:73], v[162:165], v[186:189], v[70:73]
	v_mfma_f32_16x16x32_bf16 v[38:41], v[162:165], v[194:197], v[38:41]
	v_mfma_f32_16x16x32_bf16 v[34:37], v[170:173], v[194:197], v[34:37]
	v_mfma_f32_16x16x32_bf16 v[2:5], v[170:173], v[202:205], v[2:5]
	v_mfma_f32_16x16x32_bf16 v[6:9], v[162:165], v[202:205], v[6:9]
	s_setprio 0
	s_barrier
	ds_read_b128 v[174:177], v206 offset:49152
	ds_read_b128 v[178:181], v206 offset:50176
	ds_read_b128 v[182:185], v206 offset:51200
	ds_read_b128 v[186:189], v206 offset:52224
	ds_read_b128 v[190:193], v206 offset:53248
	ds_read_b128 v[194:197], v206 offset:54272
	ds_read_b128 v[198:201], v206 offset:55296
	ds_read_b128 v[202:205], v206 offset:56320
	s_add_u32 s44, s40, 0x80
	s_addc_u32 s45, s41, 0
	s_mov_b32 m0, s53
	s_nop 0
	global_load_lds_dwordx4 v132, s[44:45]
	s_add_u32 s40, s40, 0x80080
	s_mov_b32 m0, s54
	s_nop 0
	global_load_lds_dwordx4 v134, s[44:45]
	s_addc_u32 s41, s41, 0
	s_mov_b32 m0, s57
	s_nop 0
	global_load_lds_dwordx4 v132, s[40:41]
	s_nop 0
	s_mov_b32 m0, s58
	s_nop 0
	global_load_lds_dwordx4 v134, s[40:41]
	s_nop 0
	s_waitcnt vmcnt(6)
	s_waitcnt lgkmcnt(0)
	s_barrier
	s_setprio 1
	s_waitcnt lgkmcnt(7)
	v_mfma_f32_16x16x32_bf16 v[102:105], v[142:145], v[174:177], v[102:105]
	v_mfma_f32_16x16x32_bf16 v[98:101], v[150:153], v[174:177], v[98:101]
	s_waitcnt lgkmcnt(5)
	v_mfma_f32_16x16x32_bf16 v[74:77], v[150:153], v[182:185], v[74:77]
	v_mfma_f32_16x16x32_bf16 v[78:81], v[142:145], v[182:185], v[78:81]
	s_waitcnt lgkmcnt(3)
	v_mfma_f32_16x16x32_bf16 v[46:49], v[142:145], v[190:193], v[46:49]
	v_mfma_f32_16x16x32_bf16 v[42:45], v[150:153], v[190:193], v[42:45]
	s_waitcnt lgkmcnt(1)
	v_mfma_f32_16x16x32_bf16 v[18:21], v[150:153], v[198:201], v[18:21]
	v_mfma_f32_16x16x32_bf16 v[22:25], v[142:145], v[198:201], v[22:25]
	v_mfma_f32_16x16x32_bf16 v[102:105], v[146:149], v[178:181], v[102:105]
	v_mfma_f32_16x16x32_bf16 v[98:101], v[154:157], v[178:181], v[98:101]
	v_mfma_f32_16x16x32_bf16 v[74:77], v[154:157], v[186:189], v[74:77]
	v_mfma_f32_16x16x32_bf16 v[78:81], v[146:149], v[186:189], v[78:81]
	v_mfma_f32_16x16x32_bf16 v[46:49], v[146:149], v[194:197], v[46:49]
	v_mfma_f32_16x16x32_bf16 v[42:45], v[154:157], v[194:197], v[42:45]
	s_waitcnt lgkmcnt(0)
	v_mfma_f32_16x16x32_bf16 v[18:21], v[154:157], v[202:205], v[18:21]
	v_mfma_f32_16x16x32_bf16 v[22:25], v[146:149], v[202:205], v[22:25]
	s_setprio 0
	s_setprio 1
	v_mfma_f32_16x16x32_bf16 v[110:113], v[158:161], v[174:177], v[110:113]
	v_mfma_f32_16x16x32_bf16 v[106:109], v[166:169], v[174:177], v[106:109]
	v_mfma_f32_16x16x32_bf16 v[82:85], v[166:169], v[182:185], v[82:85]
	v_mfma_f32_16x16x32_bf16 v[90:93], v[158:161], v[182:185], v[90:93]
	v_mfma_f32_16x16x32_bf16 v[62:65], v[158:161], v[190:193], v[62:65]
	v_mfma_f32_16x16x32_bf16 v[58:61], v[166:169], v[190:193], v[58:61]
	v_mfma_f32_16x16x32_bf16 v[26:29], v[166:169], v[198:201], v[26:29]
	v_mfma_f32_16x16x32_bf16 v[30:33], v[158:161], v[198:201], v[30:33]
	v_mfma_f32_16x16x32_bf16 v[110:113], v[162:165], v[178:181], v[110:113]
	v_mfma_f32_16x16x32_bf16 v[106:109], v[170:173], v[178:181], v[106:109]
	v_mfma_f32_16x16x32_bf16 v[82:85], v[170:173], v[186:189], v[82:85]
	v_mfma_f32_16x16x32_bf16 v[90:93], v[162:165], v[186:189], v[90:93]
	v_mfma_f32_16x16x32_bf16 v[62:65], v[162:165], v[194:197], v[62:65]
	v_mfma_f32_16x16x32_bf16 v[58:61], v[170:173], v[194:197], v[58:61]
	v_mfma_f32_16x16x32_bf16 v[26:29], v[170:173], v[202:205], v[26:29]
	v_mfma_f32_16x16x32_bf16 v[30:33], v[162:165], v[202:205], v[30:33]
	s_setprio 0
	s_barrier
	s_cmp_gt_u32 s65, 29
	s_cbranch_scc1 .LBB0_1027
	s_mov_b32 s65, s4
	s_branch .LBB0_998
